# grid barrier: issue the L1 acquire-invalidate at barrier entry (overlapped with arrival atomics) instead of after the release poll; no loads occur in between (1 WG per CU)
# speedup vs baseline: 1.0150x; 1.0139x over previous
; __device__ __forceinline__ unsigned xb_ld(unsigned* p)              { return __hip_atomic_load(p, __ATOMIC_RELAXED, __HIP_MEMORY_SCOPE_AGENT); }
; __device__ __forceinline__ unsigned xb_add(unsigned* p, unsigned v) { return __hip_atomic_fetch_add(p, v, __ATOMIC_RELAXED, __HIP_MEMORY_SCOPE_AGENT); }
; __device__ __forceinline__ void xcd_barrier_complete(unsigned* bar, unsigned x, unsigned& nloc, unsigned& nx) {
;     const unsigned G = gridDim.x * gridDim.y * gridDim.z;
;     unsigned sum, cnt, mine, sp = 0u;
;     for (;;) {
;         sum = 0u; cnt = 0u; mine = 0u;
; #pragma unroll
;         for (unsigned j = 0; j < 16; ++j) { const unsigned c = xb_ld(&bar[XB_XCNT(j)]); sum += c; cnt += (c > 0u) ? 1u : 0u; mine = (j == x) ? c : mine; }
;         if (sum == G) break;
;         __builtin_amdgcn_s_sleep(1);
;         if ((++sp & 255u) == 0u) { if (xb_ld(&bar[XB_TMO])) break; if (sp > XB_SPIN_CAP) { atomicAdd(&bar[XB_TMO], 1u); break; } }
;     }
;     nloc = mine > 0u ? mine : 1u; nx = cnt > 0u ? cnt : 1u;
; }
; __device__ __forceinline__ void xcd_barrier(const XcdBarrier& b) {
;     asm volatile("s_waitcnt vmcnt(0)" ::: "memory");
;     __syncthreads();
;     if (threadIdx.x == 0) {
;         unsigned* bar = b.bar;
;         __builtin_amdgcn_s_waitcnt(0);
;         unsigned nloc = b.st[0], nx = b.st[1];
;         if (nloc == 0u) { xcd_barrier_complete(bar, b.x, nloc, nx); b.st[0] = nloc; b.st[1] = nx; }
;         const unsigned old = xb_add(&bar[XB_XSUB(b.x)], 1u);
.LBB0_62:
	s_waitcnt lgkmcnt(0)
	s_getreg_b32 s3, hwreg(HW_REG_XCC_ID, 0, 4)
	s_waitcnt vmcnt(0)
	s_barrier
	s_and_saveexec_b64 s[0:1], s[68:69]
	s_xor_b64 s[0:1], exec, s[0:1]
	s_cbranch_execz .LBB0_115
	s_add_i32 s4, 0, 0x23fe0
	v_mov_b32_e32 v0, s4
	s_waitcnt vmcnt(0) expcnt(0) lgkmcnt(0)
	buffer_inv sc1
	ds_read_b32 v2, v0
	s_add_i32 s4, 0, 0x23fe4
	v_mov_b32_e32 v0, s4
	ds_read_b32 v0, v0
	s_and_b32 s3, s3, 15
	s_waitcnt lgkmcnt(1)
	v_cmp_ne_u32_e32 vcc, 0, v2
	s_cbranch_vccnz .LBB0_78
	s_load_dwordx2 s[8:9], s[70:71], 0x0
	s_load_dword s7, s[70:71], 0x8
	s_add_u32 s4, s46, 0x1000
	s_addc_u32 s5, s47, 0
	s_add_u32 s6, s46, 0x1100
	s_waitcnt lgkmcnt(0)
	s_mul_i32 s18, s9, s8
	s_mul_i32 s18, s18, s7
	s_addc_u32 s7, s47, 0
	s_add_u32 s8, s46, 0x1200
	s_addc_u32 s9, s47, 0
	s_add_u32 s10, s46, 0x1300
	s_addc_u32 s11, s47, 0
	s_mov_b32 s19, 1
	v_mov_b32_e32 v16, 0
	s_branch .LBB0_66

; __device__ __forceinline__ unsigned xb_ld(unsigned* p)              { return __hip_atomic_load(p, __ATOMIC_RELAXED, __HIP_MEMORY_SCOPE_AGENT); }
; #define XB_SPIN(cond, bar) do { unsigned _sp = 0; while (cond) { __builtin_amdgcn_s_sleep(1); \
;     if ((++_sp & 255u) == 0u) { if (xb_ld(&(bar)[XB_TMO])) break; if (_sp > XB_SPIN_CAP) { atomicAdd(&(bar)[XB_TMO], 1u); break; } } } } while (0)
; __device__ __forceinline__ void xcd_barrier(const XcdBarrier& b) {
;     ...
;         } else {
;             XB_SPIN(xb_ld(&bar[XB_XGEN(b.x)]) == gen, bar);
;             __builtin_amdgcn_fence(__ATOMIC_ACQUIRE, "agent");
;             asm volatile("s_waitcnt vmcnt(0)" ::: "memory");
.LBB0_93:
	s_or_b64 exec, exec, s[8:9]
	s_waitcnt vmcnt(0)
	s_nop 0
	s_waitcnt vmcnt(0)

; __device__ __forceinline__ unsigned xb_ld(unsigned* p)              { return __hip_atomic_load(p, __ATOMIC_RELAXED, __HIP_MEMORY_SCOPE_AGENT); }
; __device__ __forceinline__ unsigned xb_add(unsigned* p, unsigned v) { return __hip_atomic_fetch_add(p, v, __ATOMIC_RELAXED, __HIP_MEMORY_SCOPE_AGENT); }
; #define XB_SPIN(cond, bar) do { unsigned _sp = 0; while (cond) { __builtin_amdgcn_s_sleep(1); \
;     if ((++_sp & 255u) == 0u) { if (xb_ld(&(bar)[XB_TMO])) break; if (_sp > XB_SPIN_CAP) { atomicAdd(&(bar)[XB_TMO], 1u); break; } } } } while (0)
; __device__ __forceinline__ void xcd_barrier(const XcdBarrier& b) {
;     ...
;             const unsigned tg = og / nx;
;             if (og + 1u == (tg + 1u) * nx) xb_add(&bar[XB_TOPGEN], 1u);
;             else XB_SPIN(xb_ld(&bar[XB_TOPGEN]) == tg, bar);
;             __builtin_amdgcn_fence(__ATOMIC_ACQUIRE, "agent");
;             xb_add(&bar[XB_XGEN(b.x)], 1u);
;             asm volatile("s_waitcnt vmcnt(0)" ::: "memory");
.LBB0_111:
	s_or_b64 exec, exec, s[8:9]
	s_mov_b64 s[8:9], exec
	v_mbcnt_lo_u32_b32 v0, s8, 0
	v_mbcnt_hi_u32_b32 v0, s9, v0
	v_cmp_eq_u32_e32 vcc, 0, v0
	s_waitcnt vmcnt(0)
	s_nop 0
	s_and_saveexec_b64 s[10:11], vcc
	s_cbranch_execz .LBB0_113
	s_bcnt1_i32_b64 s3, s[8:9]
	v_mov_b32_e32 v0, 0x2000
	v_mov_b32_e32 v1, s3
	global_atomic_add v0, v1, s[4:5] offset:1024

; __device__ __forceinline__ unsigned xb_add(unsigned* p, unsigned v) { return __hip_atomic_fetch_add(p, v, __ATOMIC_RELAXED, __HIP_MEMORY_SCOPE_AGENT); }
; __device__ __forceinline__ void xcd_barrier(const XcdBarrier& b) {
;     asm volatile("s_waitcnt vmcnt(0)" ::: "memory");
;     __syncthreads();
;     if (threadIdx.x == 0) {
;         unsigned* bar = b.bar;
;         __builtin_amdgcn_s_waitcnt(0);
;         unsigned nloc = b.st[0], nx = b.st[1];
;         if (nloc == 0u) { xcd_barrier_complete(bar, b.x, nloc, nx); b.st[0] = nloc; b.st[1] = nx; }
;         const unsigned old = xb_add(&bar[XB_XSUB(b.x)], 1u);
.LBB0_161:
	s_getreg_b32 s4, hwreg(HW_REG_XCC_ID, 0, 4)
	s_waitcnt vmcnt(0)
	s_waitcnt vmcnt(0)
	s_barrier
	s_and_saveexec_b64 s[0:1], s[68:69]
	v_readlane_b32 s28, v254, 58
	s_xor_b64 s[0:1], exec, s[0:1]
	v_readlane_b32 s29, v254, 59
	s_cbranch_execz .LBB0_214
	v_readlane_b32 s2, v254, 42
	s_waitcnt vmcnt(0) expcnt(0) lgkmcnt(0)
	buffer_inv sc1
	s_and_b32 s10, s4, 15
	v_mov_b32_e32 v0, s2
	ds_read_b32 v2, v0
	v_readlane_b32 s2, v254, 43
	s_waitcnt lgkmcnt(0)
	v_cmp_ne_u32_e32 vcc, 0, v2
	v_mov_b32_e32 v0, s2
	ds_read_b32 v0, v0
	s_cbranch_vccnz .LBB0_177
	s_load_dwordx2 s[4:5], s[70:71], 0x0
	s_load_dword s6, s[70:71], 0x8
	s_mov_b32 s12, 1
	s_waitcnt lgkmcnt(0)
	s_mul_i32 s11, s5, s4
	s_mul_i32 s11, s11, s6
	s_branch .LBB0_165

; __device__ __forceinline__ unsigned xb_ld(unsigned* p)              { return __hip_atomic_load(p, __ATOMIC_RELAXED, __HIP_MEMORY_SCOPE_AGENT); }
; __device__ __forceinline__ unsigned xb_add(unsigned* p, unsigned v) { return __hip_atomic_fetch_add(p, v, __ATOMIC_RELAXED, __HIP_MEMORY_SCOPE_AGENT); }
; #define XB_SPIN(cond, bar) do { unsigned _sp = 0; while (cond) { __builtin_amdgcn_s_sleep(1); \
;     if ((++_sp & 255u) == 0u) { if (xb_ld(&(bar)[XB_TMO])) break; if (_sp > XB_SPIN_CAP) { atomicAdd(&(bar)[XB_TMO], 1u); break; } } } } while (0)
; __device__ __forceinline__ void xcd_barrier(const XcdBarrier& b) {
;     ...
;             const unsigned tg = og / nx;
;             if (og + 1u == (tg + 1u) * nx) xb_add(&bar[XB_TOPGEN], 1u);
;             else XB_SPIN(xb_ld(&bar[XB_TOPGEN]) == tg, bar);
;             __builtin_amdgcn_fence(__ATOMIC_ACQUIRE, "agent");
;             xb_add(&bar[XB_XGEN(b.x)], 1u);
;             asm volatile("s_waitcnt vmcnt(0)" ::: "memory");
.LBB0_210:
	s_or_b64 exec, exec, s[8:9]
	s_mov_b64 s[8:9], exec
	v_mbcnt_lo_u32_b32 v0, s8, 0
	v_mbcnt_hi_u32_b32 v0, s9, v0
	v_cmp_eq_u32_e32 vcc, 0, v0
	s_waitcnt vmcnt(0)
	s_nop 0
	s_and_saveexec_b64 s[10:11], vcc
	s_cbranch_execz .LBB0_212
	s_bcnt1_i32_b64 s8, s[8:9]
	v_mov_b32_e32 v0, s8
	global_atomic_add v190, v0, s[4:5] offset:1024

; __device__ __forceinline__ unsigned xb_add(unsigned* p, unsigned v) { return __hip_atomic_fetch_add(p, v, __ATOMIC_RELAXED, __HIP_MEMORY_SCOPE_AGENT); }
; __device__ __forceinline__ void xcd_barrier(const XcdBarrier& b) {
;     asm volatile("s_waitcnt vmcnt(0)" ::: "memory");
;     __syncthreads();
;     if (threadIdx.x == 0) {
;         unsigned* bar = b.bar;
;         __builtin_amdgcn_s_waitcnt(0);
;         unsigned nloc = b.st[0], nx = b.st[1];
;         if (nloc == 0u) { xcd_barrier_complete(bar, b.x, nloc, nx); b.st[0] = nloc; b.st[1] = nx; }
;         const unsigned old = xb_add(&bar[XB_XSUB(b.x)], 1u);
.LBB0_218:
	s_getreg_b32 s4, hwreg(HW_REG_XCC_ID, 0, 4)
	s_waitcnt vmcnt(0)
	s_mov_b64 s[48:49], 0x3000
	s_mov_b64 s[62:63], 0x3800
	s_mov_b64 s[96:97], 0x1c00
	s_mov_b64 s[50:51], 0x2c00
	s_mov_b64 s[58:59], 0x2800
	s_mov_b64 s[56:57], 0x2400
	s_mov_b64 s[54:55], 0x2000
	s_waitcnt lgkmcnt(0)
	s_barrier
	s_and_saveexec_b64 s[0:1], s[68:69]
	s_cbranch_execz .LBB0_270
	v_readlane_b32 s2, v254, 42
	s_waitcnt vmcnt(0) expcnt(0) lgkmcnt(0)
	buffer_inv sc1
	s_and_b32 s10, s4, 15
	v_mov_b32_e32 v0, s2
	ds_read_b32 v2, v0
	v_readlane_b32 s2, v254, 43
	s_waitcnt lgkmcnt(0)
	v_cmp_ne_u32_e32 vcc, 0, v2
	v_mov_b32_e32 v0, s2
	ds_read_b32 v0, v0
	s_cbranch_vccnz .LBB0_234
	s_load_dwordx2 s[4:5], s[70:71], 0x4
	s_mov_b32 s12, 1
	s_waitcnt lgkmcnt(0)
	s_mul_i32 s11, s4, s66
	s_mul_i32 s11, s11, s5
	s_branch .LBB0_222

; __device__ __forceinline__ unsigned xb_ld(unsigned* p)              { return __hip_atomic_load(p, __ATOMIC_RELAXED, __HIP_MEMORY_SCOPE_AGENT); }
; __device__ __forceinline__ unsigned xb_add(unsigned* p, unsigned v) { return __hip_atomic_fetch_add(p, v, __ATOMIC_RELAXED, __HIP_MEMORY_SCOPE_AGENT); }
; #define XB_SPIN(cond, bar) do { unsigned _sp = 0; while (cond) { __builtin_amdgcn_s_sleep(1); \
;     if ((++_sp & 255u) == 0u) { if (xb_ld(&(bar)[XB_TMO])) break; if (_sp > XB_SPIN_CAP) { atomicAdd(&(bar)[XB_TMO], 1u); break; } } } } while (0)
; __device__ __forceinline__ void xcd_barrier(const XcdBarrier& b) {
;     ...
;             const unsigned tg = og / nx;
;             if (og + 1u == (tg + 1u) * nx) xb_add(&bar[XB_TOPGEN], 1u);
;             else XB_SPIN(xb_ld(&bar[XB_TOPGEN]) == tg, bar);
;             __builtin_amdgcn_fence(__ATOMIC_ACQUIRE, "agent");
;             xb_add(&bar[XB_XGEN(b.x)], 1u);
;             asm volatile("s_waitcnt vmcnt(0)" ::: "memory");
.LBB0_267:
	s_or_b64 exec, exec, s[6:7]
	s_mov_b64 s[6:7], exec
	v_mbcnt_lo_u32_b32 v0, s6, 0
	v_mbcnt_hi_u32_b32 v0, s7, v0
	v_cmp_eq_u32_e32 vcc, 0, v0
	s_waitcnt vmcnt(0)
	s_nop 0
	s_and_saveexec_b64 s[8:9], vcc
	s_cbranch_execz .LBB0_269
	s_bcnt1_i32_b64 s6, s[6:7]
	v_mov_b32_e32 v0, s6
	global_atomic_add v190, v0, s[4:5] offset:1024

; __device__ __forceinline__ unsigned xb_add(unsigned* p, unsigned v) { return __hip_atomic_fetch_add(p, v, __ATOMIC_RELAXED, __HIP_MEMORY_SCOPE_AGENT); }
; __device__ __forceinline__ void xcd_barrier(const XcdBarrier& b) {
;     asm volatile("s_waitcnt vmcnt(0)" ::: "memory");
;     __syncthreads();
;     if (threadIdx.x == 0) {
;         unsigned* bar = b.bar;
;         __builtin_amdgcn_s_waitcnt(0);
;         unsigned nloc = b.st[0], nx = b.st[1];
;         if (nloc == 0u) { xcd_barrier_complete(bar, b.x, nloc, nx); b.st[0] = nloc; b.st[1] = nx; }
;         const unsigned old = xb_add(&bar[XB_XSUB(b.x)], 1u);
.LBB0_275:
	s_or_b64 exec, exec, s[0:1]
	s_getreg_b32 s4, hwreg(HW_REG_XCC_ID, 0, 4)
	s_waitcnt vmcnt(0)
	s_barrier
	s_and_saveexec_b64 s[0:1], s[68:69]
	s_cbranch_execz .LBB0_327
	v_readlane_b32 s2, v254, 42
	s_waitcnt vmcnt(0) expcnt(0) lgkmcnt(0)
	buffer_inv sc1
	s_and_b32 s10, s4, 15
	v_mov_b32_e32 v0, s2
	ds_read_b32 v2, v0
	v_readlane_b32 s2, v254, 43
	s_waitcnt lgkmcnt(0)
	v_cmp_ne_u32_e32 vcc, 0, v2
	v_mov_b32_e32 v0, s2
	ds_read_b32 v0, v0
	s_cbranch_vccnz .LBB0_291
	s_load_dwordx2 s[4:5], s[70:71], 0x4
	s_mov_b32 s12, 1
	s_waitcnt lgkmcnt(0)
	s_mul_i32 s11, s4, s66
	s_mul_i32 s11, s11, s5
	s_branch .LBB0_279

; __device__ __forceinline__ unsigned xb_add(unsigned* p, unsigned v) { return __hip_atomic_fetch_add(p, v, __ATOMIC_RELAXED, __HIP_MEMORY_SCOPE_AGENT); }
; __device__ __forceinline__ void xcd_barrier(const XcdBarrier& b) {
;     asm volatile("s_waitcnt vmcnt(0)" ::: "memory");
;     __syncthreads();
;     if (threadIdx.x == 0) {
;         unsigned* bar = b.bar;
;         __builtin_amdgcn_s_waitcnt(0);
;         unsigned nloc = b.st[0], nx = b.st[1];
;         if (nloc == 0u) { xcd_barrier_complete(bar, b.x, nloc, nx); b.st[0] = nloc; b.st[1] = nx; }
;         const unsigned old = xb_add(&bar[XB_XSUB(b.x)], 1u);
.LBB0_339:
	s_getreg_b32 s4, hwreg(HW_REG_XCC_ID, 0, 4)
	s_waitcnt vmcnt(0)
	s_barrier
	s_and_saveexec_b64 s[0:1], s[68:69]
	v_readlane_b32 s24, v254, 63
	s_xor_b64 s[0:1], exec, s[0:1]
	v_readlane_b32 s25, v255, 0
	s_cbranch_execz .LBB0_392
	v_readlane_b32 s2, v254, 42
	s_waitcnt vmcnt(0) expcnt(0) lgkmcnt(0)
	buffer_inv sc1
	s_and_b32 s10, s4, 15
	v_mov_b32_e32 v0, s2
	ds_read_b32 v2, v0
	v_readlane_b32 s2, v254, 43
	s_waitcnt lgkmcnt(0)
	v_cmp_ne_u32_e32 vcc, 0, v2
	v_mov_b32_e32 v0, s2
	ds_read_b32 v0, v0
	s_cbranch_vccnz .LBB0_355
	s_load_dwordx2 s[4:5], s[70:71], 0x4
	s_mov_b32 s12, 1
	s_waitcnt lgkmcnt(0)
	s_mul_i32 s11, s4, s66
	s_mul_i32 s11, s11, s5
	s_branch .LBB0_343

; __device__ __forceinline__ unsigned xb_add(unsigned* p, unsigned v) { return __hip_atomic_fetch_add(p, v, __ATOMIC_RELAXED, __HIP_MEMORY_SCOPE_AGENT); }
; __device__ __forceinline__ void xcd_barrier(const XcdBarrier& b) {
;     asm volatile("s_waitcnt vmcnt(0)" ::: "memory");
;     __syncthreads();
;     if (threadIdx.x == 0) {
;         unsigned* bar = b.bar;
;         __builtin_amdgcn_s_waitcnt(0);
;         unsigned nloc = b.st[0], nx = b.st[1];
;         if (nloc == 0u) { xcd_barrier_complete(bar, b.x, nloc, nx); b.st[0] = nloc; b.st[1] = nx; }
;         const unsigned old = xb_add(&bar[XB_XSUB(b.x)], 1u);
.LBB0_469:
	s_getreg_b32 s4, hwreg(HW_REG_XCC_ID, 0, 4)
	s_waitcnt vmcnt(0)
	s_waitcnt lgkmcnt(0)
	s_barrier
	s_and_saveexec_b64 s[0:1], s[68:69]
	s_cbranch_execz .LBB0_521
	v_readlane_b32 s2, v254, 42
	s_waitcnt vmcnt(0) expcnt(0) lgkmcnt(0)
	buffer_inv sc1
	s_and_b32 s10, s4, 15
	v_mov_b32_e32 v0, s2
	ds_read_b32 v2, v0
	v_readlane_b32 s2, v254, 43
	s_waitcnt lgkmcnt(0)
	v_cmp_ne_u32_e32 vcc, 0, v2
	v_mov_b32_e32 v0, s2
	ds_read_b32 v0, v0
	s_cbranch_vccnz .LBB0_485
	s_load_dwordx2 s[4:5], s[70:71], 0x4
	s_mov_b32 s12, 1
	s_waitcnt lgkmcnt(0)
	s_mul_i32 s11, s4, s42
	s_mul_i32 s11, s11, s5
	s_branch .LBB0_473

; __device__ __forceinline__ unsigned xb_add(unsigned* p, unsigned v) { return __hip_atomic_fetch_add(p, v, __ATOMIC_RELAXED, __HIP_MEMORY_SCOPE_AGENT); }
; __device__ __forceinline__ void xcd_barrier(const XcdBarrier& b) {
;     asm volatile("s_waitcnt vmcnt(0)" ::: "memory");
;     __syncthreads();
;     if (threadIdx.x == 0) {
;         unsigned* bar = b.bar;
;         __builtin_amdgcn_s_waitcnt(0);
;         unsigned nloc = b.st[0], nx = b.st[1];
;         if (nloc == 0u) { xcd_barrier_complete(bar, b.x, nloc, nx); b.st[0] = nloc; b.st[1] = nx; }
;         const unsigned old = xb_add(&bar[XB_XSUB(b.x)], 1u);
.LBB0_544:
	s_or_b64 exec, exec, s[0:1]
	s_getreg_b32 s4, hwreg(HW_REG_XCC_ID, 0, 4)
	s_waitcnt vmcnt(0)
	s_barrier
	s_and_saveexec_b64 s[0:1], s[68:69]
	s_cbranch_execz .LBB0_596
	v_readlane_b32 s2, v254, 42
	s_waitcnt vmcnt(0) expcnt(0) lgkmcnt(0)
	buffer_inv sc1
	s_and_b32 s10, s4, 15
	v_mov_b32_e32 v0, s2
	ds_read_b32 v2, v0
	v_readlane_b32 s2, v254, 43
	s_waitcnt lgkmcnt(0)
	v_cmp_ne_u32_e32 vcc, 0, v2
	v_mov_b32_e32 v0, s2
	ds_read_b32 v0, v0
	s_cbranch_vccnz .LBB0_560
	s_load_dwordx2 s[4:5], s[70:71], 0x4
	s_mov_b32 s12, 1
	s_waitcnt lgkmcnt(0)
	s_mul_i32 s11, s4, s42
	s_mul_i32 s11, s11, s5
	s_branch .LBB0_548

; __device__ __forceinline__ unsigned xb_add(unsigned* p, unsigned v) { return __hip_atomic_fetch_add(p, v, __ATOMIC_RELAXED, __HIP_MEMORY_SCOPE_AGENT); }
; __device__ __forceinline__ void xcd_barrier(const XcdBarrier& b) {
;     asm volatile("s_waitcnt vmcnt(0)" ::: "memory");
;     __syncthreads();
;     if (threadIdx.x == 0) {
;         unsigned* bar = b.bar;
;         __builtin_amdgcn_s_waitcnt(0);
;         unsigned nloc = b.st[0], nx = b.st[1];
;         if (nloc == 0u) { xcd_barrier_complete(bar, b.x, nloc, nx); b.st[0] = nloc; b.st[1] = nx; }
;         const unsigned old = xb_add(&bar[XB_XSUB(b.x)], 1u);
.LBB0_606:
	s_getreg_b32 s4, hwreg(HW_REG_XCC_ID, 0, 4)
	s_waitcnt vmcnt(0)
	s_barrier
	s_and_saveexec_b64 s[0:1], s[68:69]
	s_xor_b64 s[0:1], exec, s[0:1]
	s_cbranch_execz .LBB0_659
	v_readlane_b32 s2, v254, 42
	s_waitcnt vmcnt(0) expcnt(0) lgkmcnt(0)
	buffer_inv sc1
	s_and_b32 s10, s4, 15
	v_mov_b32_e32 v0, s2
	ds_read_b32 v2, v0
	v_readlane_b32 s2, v254, 43
	s_waitcnt lgkmcnt(0)
	v_cmp_ne_u32_e32 vcc, 0, v2
	v_mov_b32_e32 v0, s2
	ds_read_b32 v0, v0
	s_cbranch_vccnz .LBB0_622
	s_load_dwordx2 s[4:5], s[70:71], 0x4
	s_mov_b32 s12, 1
	s_waitcnt lgkmcnt(0)
	s_mul_i32 s11, s4, s42
	s_mul_i32 s11, s11, s5
	s_branch .LBB0_610

; __device__ __forceinline__ unsigned xb_add(unsigned* p, unsigned v) { return __hip_atomic_fetch_add(p, v, __ATOMIC_RELAXED, __HIP_MEMORY_SCOPE_AGENT); }
; __device__ __forceinline__ void xcd_barrier(const XcdBarrier& b) {
;     asm volatile("s_waitcnt vmcnt(0)" ::: "memory");
;     __syncthreads();
;     if (threadIdx.x == 0) {
;         unsigned* bar = b.bar;
;         __builtin_amdgcn_s_waitcnt(0);
;         unsigned nloc = b.st[0], nx = b.st[1];
;         if (nloc == 0u) { xcd_barrier_complete(bar, b.x, nloc, nx); b.st[0] = nloc; b.st[1] = nx; }
;         const unsigned old = xb_add(&bar[XB_XSUB(b.x)], 1u);
.LBB0_680:
	s_getreg_b32 s4, hwreg(HW_REG_XCC_ID, 0, 4)
	s_waitcnt vmcnt(0)
	s_barrier
	s_and_saveexec_b64 s[0:1], s[68:69]
	s_xor_b64 s[0:1], exec, s[0:1]
	s_cbranch_execz .LBB0_733
	v_readlane_b32 s2, v254, 42
	s_waitcnt vmcnt(0) expcnt(0) lgkmcnt(0)
	buffer_inv sc1
	s_and_b32 s10, s4, 15
	v_mov_b32_e32 v0, s2
	ds_read_b32 v2, v0
	v_readlane_b32 s2, v254, 43
	s_waitcnt lgkmcnt(0)
	v_cmp_ne_u32_e32 vcc, 0, v2
	v_mov_b32_e32 v0, s2
	ds_read_b32 v0, v0
	s_cbranch_vccnz .LBB0_696
	s_load_dwordx2 s[4:5], s[70:71], 0x0
	s_load_dword s6, s[70:71], 0x8
	s_mov_b32 s12, 1
	s_waitcnt lgkmcnt(0)
	s_mul_i32 s11, s5, s4
	s_mul_i32 s11, s11, s6
	s_branch .LBB0_684

; __device__ __forceinline__ unsigned xb_add(unsigned* p, unsigned v) { return __hip_atomic_fetch_add(p, v, __ATOMIC_RELAXED, __HIP_MEMORY_SCOPE_AGENT); }
; __device__ __forceinline__ void xcd_barrier(const XcdBarrier& b) {
;     asm volatile("s_waitcnt vmcnt(0)" ::: "memory");
;     __syncthreads();
;     if (threadIdx.x == 0) {
;         unsigned* bar = b.bar;
;         __builtin_amdgcn_s_waitcnt(0);
;         unsigned nloc = b.st[0], nx = b.st[1];
;         if (nloc == 0u) { xcd_barrier_complete(bar, b.x, nloc, nx); b.st[0] = nloc; b.st[1] = nx; }
;         const unsigned old = xb_add(&bar[XB_XSUB(b.x)], 1u);
.LBB0_829:
	s_getreg_b32 s4, hwreg(HW_REG_XCC_ID, 0, 4)
	s_waitcnt vmcnt(0)
	s_waitcnt vmcnt(0) lgkmcnt(0)
	s_barrier
	s_and_saveexec_b64 s[0:1], s[68:69]
	v_readlane_b32 s26, v254, 49
	v_readlane_b32 s80, v254, 51
	s_xor_b64 s[0:1], exec, s[0:1]
	v_readlane_b32 s27, v254, 50
	v_readlane_b32 s81, v254, 52
	s_cbranch_execz .LBB0_882
	v_readlane_b32 s2, v254, 42
	s_waitcnt vmcnt(0) expcnt(0) lgkmcnt(0)
	buffer_inv sc1
	s_and_b32 s10, s4, 15
	v_mov_b32_e32 v0, s2
	ds_read_b32 v2, v0
	v_readlane_b32 s2, v254, 43
	s_waitcnt lgkmcnt(0)
	v_cmp_ne_u32_e32 vcc, 0, v2
	v_mov_b32_e32 v0, s2
	ds_read_b32 v0, v0
	s_cbranch_vccnz .LBB0_845
	s_load_dwordx2 s[4:5], s[70:71], 0x0
	s_load_dword s6, s[70:71], 0x8
	s_mov_b32 s12, 1
	s_waitcnt lgkmcnt(0)
	s_mul_i32 s11, s5, s4
	s_mul_i32 s11, s11, s6
	s_branch .LBB0_833

; __device__ __forceinline__ unsigned xb_add(unsigned* p, unsigned v) { return __hip_atomic_fetch_add(p, v, __ATOMIC_RELAXED, __HIP_MEMORY_SCOPE_AGENT); }
; #define GSYNC() do { XcdBarrier b_; b_.bar = (unsigned*)args.ws; b_.x = xb_xcc_id(); b_.st = (volatile LAS unsigned*)((LAS unsigned char*)lds + LDS_BYTES - 64) + 8; xcd_barrier(b_); if constexpr ((DUP) & 0x10000) xcd_barrier(b_); } while (0)
; __device__ __forceinline__ void xcd_barrier(const XcdBarrier& b) {
;     asm volatile("s_waitcnt vmcnt(0)" ::: "memory");
;     __syncthreads();
;     if (threadIdx.x == 0) {
;         unsigned* bar = b.bar;
;         __builtin_amdgcn_s_waitcnt(0);
;         unsigned nloc = b.st[0], nx = b.st[1];
;         if (nloc == 0u) { xcd_barrier_complete(bar, b.x, nloc, nx); b.st[0] = nloc; b.st[1] = nx; }
;         const unsigned old = xb_add(&bar[XB_XSUB(b.x)], 1u);
; __global__ void __launch_bounds__(NTHR, 2) fwd_megakernel(Args args) {
;     ...
;         if (even) {
;             GSYNC();
.LBB0_906:
	v_readlane_b32 s0, v254, 61
	v_readlane_b32 s1, v254, 62
	s_mov_b64 s[6:7], -1
	s_andn2_b64 vcc, exec, s[0:1]
	s_mov_b64 s[0:1], -1
	s_cbranch_vccnz .LBB0_118
	s_getreg_b32 s4, hwreg(HW_REG_XCC_ID, 0, 4)
	s_waitcnt vmcnt(0)
	s_barrier
	s_and_saveexec_b64 s[0:1], s[68:69]
	s_cbranch_execz .LBB0_959
	v_readlane_b32 s2, v254, 42
	s_waitcnt vmcnt(0) expcnt(0) lgkmcnt(0)
	buffer_inv sc1
	s_and_b32 s12, s4, 15
	v_mov_b32_e32 v0, s2
	ds_read_b32 v2, v0
	v_readlane_b32 s2, v254, 43
	s_waitcnt lgkmcnt(0)
	v_cmp_ne_u32_e32 vcc, 0, v2
	v_mov_b32_e32 v0, s2
	ds_read_b32 v0, v0
	s_cbranch_vccnz .LBB0_923
	s_load_dwordx2 s[4:5], s[70:71], 0x0
	s_load_dword s8, s[70:71], 0x8
	s_mov_b32 s14, 1
	s_waitcnt lgkmcnt(0)
	s_mul_i32 s13, s5, s4
	s_mul_i32 s13, s13, s8
	s_branch .LBB0_911

; __device__ __forceinline__ unsigned xb_ld(unsigned* p)              { return __hip_atomic_load(p, __ATOMIC_RELAXED, __HIP_MEMORY_SCOPE_AGENT); }
; #define XB_SPIN(cond, bar) do { unsigned _sp = 0; while (cond) { __builtin_amdgcn_s_sleep(1); \
;     if ((++_sp & 255u) == 0u) { if (xb_ld(&(bar)[XB_TMO])) break; if (_sp > XB_SPIN_CAP) { atomicAdd(&(bar)[XB_TMO], 1u); break; } } } } while (0)
; __device__ __forceinline__ void xcd_barrier(const XcdBarrier& b) {
;     ...
;         } else {
;             XB_SPIN(xb_ld(&bar[XB_XGEN(b.x)]) == gen, bar);
;             __builtin_amdgcn_fence(__ATOMIC_ACQUIRE, "agent");
;             asm volatile("s_waitcnt vmcnt(0)" ::: "memory");
.LBB0_938:
	s_or_b64 exec, exec, s[10:11]
	s_waitcnt vmcnt(0)
	s_nop 0
	s_waitcnt vmcnt(0)

; __device__ __forceinline__ unsigned xb_add(unsigned* p, unsigned v) { return __hip_atomic_fetch_add(p, v, __ATOMIC_RELAXED, __HIP_MEMORY_SCOPE_AGENT); }
; #define GSYNC() do { XcdBarrier b_; b_.bar = (unsigned*)args.ws; b_.x = xb_xcc_id(); b_.st = (volatile LAS unsigned*)((LAS unsigned char*)lds + LDS_BYTES - 64) + 8; xcd_barrier(b_); if constexpr ((DUP) & 0x10000) xcd_barrier(b_); } while (0)
; __device__ __forceinline__ void xcd_barrier(const XcdBarrier& b) {
;     asm volatile("s_waitcnt vmcnt(0)" ::: "memory");
;     __syncthreads();
;     if (threadIdx.x == 0) {
;         unsigned* bar = b.bar;
;         __builtin_amdgcn_s_waitcnt(0);
;         unsigned nloc = b.st[0], nx = b.st[1];
;         if (nloc == 0u) { xcd_barrier_complete(bar, b.x, nloc, nx); b.st[0] = nloc; b.st[1] = nx; }
;         const unsigned old = xb_add(&bar[XB_XSUB(b.x)], 1u);
; __global__ void __launch_bounds__(NTHR, 2) fwd_megakernel(Args args) {
;     ...
;             GSYNC();
.LBB0_962:
	s_getreg_b32 s4, hwreg(HW_REG_XCC_ID, 0, 4)
	s_waitcnt vmcnt(0)
	s_waitcnt lgkmcnt(0)
	s_barrier
	s_and_saveexec_b64 s[0:1], s[68:69]
	s_cbranch_execz .LBB0_117
	v_readlane_b32 s2, v254, 42
	s_waitcnt vmcnt(0) expcnt(0) lgkmcnt(0)
	buffer_inv sc1
	s_and_b32 s12, s4, 15
	v_mov_b32_e32 v0, s2
	ds_read_b32 v2, v0
	v_readlane_b32 s2, v254, 43
	s_waitcnt lgkmcnt(0)
	v_cmp_ne_u32_e32 vcc, 0, v2
	v_mov_b32_e32 v0, s2
	ds_read_b32 v0, v0
	s_cbranch_vccnz .LBB0_978
	s_load_dwordx2 s[4:5], s[70:71], 0x4
	s_waitcnt lgkmcnt(0)
	s_mul_i32 s13, s4, s14
	s_mul_i32 s13, s13, s5
	s_mov_b32 s14, 1
	s_branch .LBB0_966

; __device__ __forceinline__ unsigned xb_ld(unsigned* p)              { return __hip_atomic_load(p, __ATOMIC_RELAXED, __HIP_MEMORY_SCOPE_AGENT); }
; __device__ __forceinline__ unsigned xb_add(unsigned* p, unsigned v) { return __hip_atomic_fetch_add(p, v, __ATOMIC_RELAXED, __HIP_MEMORY_SCOPE_AGENT); }
; #define XB_SPIN(cond, bar) do { unsigned _sp = 0; while (cond) { __builtin_amdgcn_s_sleep(1); \
;     if ((++_sp & 255u) == 0u) { if (xb_ld(&(bar)[XB_TMO])) break; if (_sp > XB_SPIN_CAP) { atomicAdd(&(bar)[XB_TMO], 1u); break; } } } } while (0)
; __device__ __forceinline__ void xcd_barrier(const XcdBarrier& b) {
;     ...
;             const unsigned tg = og / nx;
;             if (og + 1u == (tg + 1u) * nx) xb_add(&bar[XB_TOPGEN], 1u);
;             else XB_SPIN(xb_ld(&bar[XB_TOPGEN]) == tg, bar);
;             __builtin_amdgcn_fence(__ATOMIC_ACQUIRE, "agent");
;             xb_add(&bar[XB_XGEN(b.x)], 1u);
;             asm volatile("s_waitcnt vmcnt(0)" ::: "memory");
.LBB0_1011:
	s_or_b64 exec, exec, s[8:9]
	s_mov_b64 s[8:9], exec
	v_mbcnt_lo_u32_b32 v0, s8, 0
	v_mbcnt_hi_u32_b32 v0, s9, v0
	v_cmp_eq_u32_e32 vcc, 0, v0
	s_waitcnt vmcnt(0)
	s_nop 0
	s_and_saveexec_b64 s[10:11], vcc
	s_cbranch_execnz .LBB0_1012
	s_getpc_b64 s[98:99]
